# attention tile-loop head: wave-uniform test feeds the branch from SCC directly (s_and_b64 vcc dropped)
# speedup vs baseline: 1.0027x; 1.0027x over previous
; DI void attn_item(const Params& p, int item, char* smem) {
;     ...
;   for (int kt = 0; kt < nkt; kt += 2) {
;     if (kt + 2 < nkt) gload(b, kt + 2);
.LBB0_529:
	s_add_i32 s11, s12, 2
	s_cmp_lt_u32 s11, s10
	s_cselect_b64 s[6:7], -1, 0
	s_cmp_ge_u32 s11, s10
	s_cselect_b64 s[4:5], -1, 0
	s_cbranch_scc1 .LBB0_531
	global_load_dwordx4 v[124:127], v146, s[22:23]
	global_load_dwordx4 v[128:131], v144, s[22:23]
	global_load_dwordx4 v[132:135], v142, s[22:23]
	global_load_dwordx4 v[2:5], v140, s[26:27] offset:256
	global_load_dwordx4 v[6:9], v140, s[28:29] offset:256
